# ladder + reorder + no per-block setprio + one static s_setprio 1 for waves 4-7 at each phase start
# baseline (speedup 1.0000x reference)
.LBB0_7:
	s_load_dword s94, s[0:1], 0x100
	s_mov_b64 s[48:49], s[0:1]
	s_mov_b32 s14, s26
	v_mov_b32_e32 v231, v179
	v_readfirstlane_b32 s98, v179
	s_lshr_b32 s98, s98, 8
	s_cmp_eq_u32 s98, 1
	s_cbranch_scc0 .Lprio_skip
	s_setprio 1
.Lprio_skip:
	s_waitcnt lgkmcnt(0)
	s_load_dwordx4 s[20:23], s[48:49], 0xf0
	s_mov_b64 s[12:13], -1
	s_mov_b64 s[2:3], 0
	s_cmp_lt_i32 s43, 9
	s_mov_b64 s[16:17], 0
	s_cbranch_scc1 .LBB0_39
	s_mov_b64 s[18:19], -1
	s_mov_b64 s[8:9], 0
	s_cmp_lt_i32 s43, 13
	s_mov_b64 s[12:13], 0
	s_cbranch_scc1 .LBB0_25
	s_mov_b64 s[10:11], -1
	s_mov_b64 s[6:7], 0
	s_cmp_gt_i32 s43, 14
	s_cbranch_scc0 .LBB0_18
	s_mov_b64 s[52:53], -1
	s_mov_b64 s[4:5], 0
	s_cmp_gt_i32 s43, 15
	s_cbranch_scc0 .LBB0_15
	s_mov_b64 s[10:11], 0
	s_mov_b64 s[12:13], -1
	s_cmp_gt_i32 s43, 16
	s_cbranch_scc0 .LBB0_15
	s_cmp_lg_u32 s43, 17
	s_mov_b64 s[16:17], -1
	s_cbranch_scc0 .LBB0_14
	s_mov_b64 s[16:17], 0
